# v10 plus: softmax row sums with packed f32 adds
# speedup vs baseline: 1.0256x; 1.0071x over previous
; #define PG8_LAS __attribute__((address_space(3)))
; __device__ __forceinline__ unsigned cvt_pk_bf16(float lo, float hi) { const f32x2c v = {lo, hi}; const bf16x2c b = __builtin_convertvector(v, bf16x2c); return __builtin_bit_cast(unsigned, b); }
; __device__ void phase_attn(KP p, PG8_LAS unsigned char* lds, float* ldsf, int tid_in) {
;     ...
;                         for (int f = 0; f < 4; ++f)
; #pragma unroll
;                             for (int r = 0; r < 4; ++r) { const float e = __builtin_amdgcn_exp2f(st[f][nb][r] - mn); st[f][nb][r] = e; ps += e; }
;                         lrun[nb] = lrun[nb] * al + ps;
; #pragma unroll
;                         for (int df = 0; df < 4; ++df) o[df][nb] *= al;
;                     }
; #pragma unroll
;                     for (int kk = 0; kk < 2; ++kk) {
;                         bf16x8 pb[2];
; #pragma unroll
;                         for (int nb = 0; nb < 2; ++nb) {
;                             u32x4v t; t[0] = cvt_pk_bf16(st[2 * kk][nb][0], st[2 * kk][nb][1]); t[1] = cvt_pk_bf16(st[2 * kk][nb][2], st[2 * kk][nb][3]);
;                             t[2] = cvt_pk_bf16(st[2 * kk + 1][nb][0], st[2 * kk + 1][nb][1]); t[3] = cvt_pk_bf16(st[2 * kk + 1][nb][2], st[2 * kk + 1][nb][3]);
;                             pb[nb] = __builtin_bit_cast(bf16x8, t);
;                         }
; #pragma unroll
;                         for (int df = 0; df < 4; ++df) {
;                             const u32x2 v0 = *(const PG8_LAS u32x2*)(kb + va_rd + df * 16 * VS * 2 + kk * 64), v1 = *(const PG8_LAS u32x2*)(kb + va_rd + df * 16 * VS * 2 + kk * 64 + 32);
;                             u32x4v t; t[0] = v0[0]; t[1] = v0[1]; t[2] = v1[0]; t[3] = v1[1];
;                             const bf16x8 a = __builtin_bit_cast(bf16x8, t);
; #pragma unroll
;                             for (int nb = 0; nb < 2; ++nb) o[df][nb] = __builtin_amdgcn_mfma_f32_16x16x32_bf16(a, pb[nb], o[df][nb], 0, 0, 0);
;                         }
.Lat_cont0_1:
	v_mfma_f32_16x16x32_bf16 v[84:87], v[202:205], v[42:45], v[230:233]
	v_exp_f32_e32 v134, v134
	v_exp_f32_e32 v135, v135
	v_mfma_f32_16x16x32_bf16 v[84:87], v[206:209], v[30:33], v[84:87]
	v_exp_f32_e32 v136, v136
	v_exp_f32_e32 v137, v137
	v_mfma_f32_16x16x32_bf16 v[84:87], v[210:213], v[34:37], v[84:87]
	v_exp_f32_e32 v138, v138
	v_exp_f32_e32 v139, v139
	v_mfma_f32_16x16x32_bf16 v[88:91], v[214:217], v[42:45], v[230:233]
	v_exp_f32_e32 v140, v140
	v_exp_f32_e32 v141, v141
	v_mfma_f32_16x16x32_bf16 v[88:91], v[218:221], v[30:33], v[88:91]
	v_exp_f32_e32 v142, v142
	v_exp_f32_e32 v143, v143
	v_mfma_f32_16x16x32_bf16 v[88:91], v[222:225], v[34:37], v[88:91]
	v_exp_f32_e32 v144, v144
	v_exp_f32_e32 v145, v145
	v_exp_f32_e32 v146, v146
	v_exp_f32_e32 v147, v147
	v_exp_f32_e32 v148, v148
	v_exp_f32_e32 v149, v149
	ds_read_b64 v[178:179], v92 offset:13312
	ds_read_b64 v[180:181], v92 offset:13344
	ds_read_b64 v[182:183], v92 offset:15616
	ds_read_b64 v[184:185], v92 offset:15648
	ds_read_b64 v[186:187], v92 offset:17920
	ds_read_b64 v[188:189], v92 offset:17952
	ds_read_b64 v[190:191], v92 offset:20224
	ds_read_b64 v[192:193], v92 offset:20256
	ds_read_b64 v[194:195], v92 offset:13376
	ds_read_b64 v[196:197], v92 offset:13408
	ds_read_b64 v[198:199], v92 offset:15680
	ds_read_b64 v[200:201], v92 offset:15712
	ds_read_b64 v[202:203], v92 offset:17984
	ds_read_b64 v[204:205], v92 offset:18016
	ds_read_b64 v[206:207], v92 offset:20288
	ds_read_b64 v[208:209], v92 offset:20320
	v_max3_f32 v157, v76, v77, v78
	v_max3_f32 v157, v157, v79, v80
	v_max3_f32 v157, v157, v81, v82
	v_max3_f32 v157, v157, v83, v84
	v_max3_f32 v157, v157, v85, v86
	v_max3_f32 v157, v157, v87, v88
	v_max3_f32 v157, v157, v89, v90
	v_max_f32_e32 v157, v157, v91
	v_cmp_lt_f32_e32 vcc, 0x41000000, v157
	v_pk_add_f32 v[162:163], v[134:135], v[136:137]
	v_pk_add_f32 v[174:175], v[138:139], v[140:141]
	s_or_b64 vcc, vcc, s[14:15]
	s_cbranch_vccnz .Lat_resc1_1
.Lat_cont1_1:
	v_pk_add_f32 v[162:163], v[162:163], v[142:143]
	v_pk_add_f32 v[174:175], v[174:175], v[144:145]
	v_pk_add_f32 v[162:163], v[162:163], v[146:147]
	v_pk_add_f32 v[174:175], v[174:175], v[148:149]
	v_pk_add_f32 v[162:163], v[162:163], v[174:175]
	v_add_f32_e32 v154, v162, v163
	v_add_f32_e32 v125, v125, v154
	v_cvt_pk_bf16_f32 v134, v134, v135
	v_cvt_pk_bf16_f32 v135, v136, v137
	v_cvt_pk_bf16_f32 v136, v138, v139
	v_cvt_pk_bf16_f32 v137, v140, v141
	v_cvt_pk_bf16_f32 v142, v142, v143
	v_cvt_pk_bf16_f32 v143, v144, v145
	v_cvt_pk_bf16_f32 v144, v146, v147
	v_cvt_pk_bf16_f32 v145, v148, v149
	s_waitcnt lgkmcnt(8)
	v_exp_f32_e32 v76, v76
	v_exp_f32_e32 v77, v77
	v_mfma_f32_16x16x32_bf16 v[54:57], v[178:181], v[134:137], v[54:57]
	v_exp_f32_e32 v78, v78
	v_exp_f32_e32 v79, v79
	v_mfma_f32_16x16x32_bf16 v[58:61], v[182:185], v[134:137], v[58:61]
	v_exp_f32_e32 v80, v80
	v_exp_f32_e32 v81, v81
	v_mfma_f32_16x16x32_bf16 v[62:65], v[186:189], v[134:137], v[62:65]
	v_exp_f32_e32 v82, v82
	v_exp_f32_e32 v83, v83
	v_mfma_f32_16x16x32_bf16 v[66:69], v[190:193], v[134:137], v[66:69]
	v_exp_f32_e32 v84, v84
	v_exp_f32_e32 v85, v85
	s_waitcnt lgkmcnt(0)
	v_mfma_f32_16x16x32_bf16 v[54:57], v[194:197], v[142:145], v[54:57]
	v_exp_f32_e32 v86, v86
	v_exp_f32_e32 v87, v87
	v_mfma_f32_16x16x32_bf16 v[58:61], v[198:201], v[142:145], v[58:61]
	v_exp_f32_e32 v88, v88
	v_exp_f32_e32 v89, v89
	v_mfma_f32_16x16x32_bf16 v[62:65], v[202:205], v[142:145], v[62:65]
	v_exp_f32_e32 v90, v90
	v_exp_f32_e32 v91, v91
	v_mfma_f32_16x16x32_bf16 v[66:69], v[206:209], v[142:145], v[66:69]
	v_pk_add_f32 v[176:177], v[76:77], v[78:79]
	v_pk_add_f32 v[70:71], v[80:81], v[82:83]
	v_pk_add_f32 v[176:177], v[176:177], v[84:85]
	v_pk_add_f32 v[70:71], v[70:71], v[86:87]
	v_pk_add_f32 v[176:177], v[176:177], v[88:89]
	v_pk_add_f32 v[70:71], v[70:71], v[90:91]
	v_pk_add_f32 v[176:177], v[176:177], v[70:71]
	v_add_f32_e32 v155, v176, v177
	v_add_f32_e32 v124, v124, v155
	v_cvt_pk_bf16_f32 v76, v76, v77
	v_cvt_pk_bf16_f32 v77, v78, v79
	v_cvt_pk_bf16_f32 v78, v80, v81
	v_cvt_pk_bf16_f32 v79, v82, v83
	v_cvt_pk_bf16_f32 v84, v84, v85
	v_cvt_pk_bf16_f32 v85, v86, v87
	v_mfma_f32_16x16x32_bf16 v[4:7], v[178:181], v[76:79], v[4:7]
	v_cvt_pk_bf16_f32 v86, v88, v89
	v_mfma_f32_16x16x32_bf16 v[10:13], v[182:185], v[76:79], v[10:13]
	v_cvt_pk_bf16_f32 v87, v90, v91
	v_mfma_f32_16x16x32_bf16 v[14:17], v[186:189], v[76:79], v[14:17]
	v_mfma_f32_16x16x32_bf16 v[18:21], v[190:193], v[76:79], v[18:21]
	v_mfma_f32_16x16x32_bf16 v[4:7], v[194:197], v[84:87], v[4:7]
	v_mfma_f32_16x16x32_bf16 v[10:13], v[198:201], v[84:87], v[10:13]
	v_mfma_f32_16x16x32_bf16 v[14:17], v[202:205], v[84:87], v[14:17]
	v_mfma_f32_16x16x32_bf16 v[18:21], v[206:209], v[84:87], v[18:21]
	s_branch .Lat_end_1
